# grid barriers 12 and 13 (around layer 1 gate|up) become XCC-local when a run-time census shows every blockIdx%8 group sits on one XCC: leaders skip the L2 writeback and the cross-XCC round
# speedup vs baseline: 1.0009x; 1.0009x over previous
_Z14fwd_megakernel4Args:
	v_mov_b32_e32 v1, v0
	v_mov_b32_e32 v2, 0
	v_lshl_add_u32 v1, v0, 2, 0
	v_add_u32_e32 v1, 0x20000, v1
	ds_write2st64_b32 v1, v2, v2 offset1:8
	ds_write2st64_b32 v1, v2, v2 offset0:16 offset1:24
	v_or_b32_e32 v1, 0x800, v0
	s_mov_b64 s[4:5], -1
	s_and_saveexec_b64 s[6:7], s[4:5]
	v_lshl_add_u32 v3, v1, 2, 0
	v_add_u32_e32 v3, 0x20000, v3
	ds_write_b32 v3, v2
	s_or_b64 exec, exec, s[6:7]
	s_load_dwordx2 s[34:35], s[0:1], 0xb0
	s_load_dwordx4 s[8:11], s[0:1], 0xa0
	s_load_dwordx8 s[52:59], s[0:1], 0x80
	s_waitcnt lgkmcnt(0)
	v_writelane_b32 v250, s8, 0
	s_nop 1
	v_writelane_b32 v250, s9, 1
	v_writelane_b32 v250, s10, 2
	v_writelane_b32 v250, s11, 3
	s_and_saveexec_b64 s[6:7], s[4:5]
	s_add_i32 s3, 0, 0x20000
	v_lshl_add_u32 v1, v1, 2, s3
	v_mov_b32_e32 v2, 0
	ds_write_b32 v1, v2 offset:2048
	s_or_b64 exec, exec, s[6:7]
	v_or_b32_e32 v1, 0xc00, v0
	v_cmp_gt_u32_e64 s[4:5], 7, 6
	v_cmp_gt_u32_e64 s[8:9], 7, 5
	s_and_saveexec_b64 s[6:7], s[8:9]
	v_lshl_add_u32 v2, v1, 2, 0
	v_add_u32_e32 v2, 0x20000, v2
	v_mov_b32_e32 v3, 0
	ds_write_b32 v2, v3
	s_or_b64 exec, exec, s[6:7]
	s_and_saveexec_b64 s[6:7], s[4:5]
	s_add_i32 s3, 0, 0x20000
	v_lshl_add_u32 v1, v1, 2, s3
	v_mov_b32_e32 v2, 0
	ds_write_b32 v1, v2 offset:2048
	s_or_b64 exec, exec, s[6:7]
	s_add_u32 s64, s34, 0x4000
	s_waitcnt lgkmcnt(0)
	s_barrier
	s_addc_u32 s65, s35, 0
	s_getreg_b32 s3, hwreg(HW_REG_XCC_ID, 0, 4)
	v_cmp_eq_u32_e64 s[6:7], 0, v0
	s_mov_b64 s[4:5], exec
	s_nop 0
	v_writelane_b32 v250, s6, 4
	s_nop 1
	v_writelane_b32 v250, s7, 5
	s_and_b64 s[6:7], s[4:5], s[6:7]
	s_mov_b64 exec, s[6:7]
	s_cbranch_execz .LBB0_11
	s_mov_b64 s[6:7], exec
	v_mbcnt_lo_u32_b32 v1, s6, 0
	v_mbcnt_hi_u32_b32 v1, s7, v1
	v_cmp_eq_u32_e32 vcc, 0, v1
	s_and_b64 s[8:9], exec, vcc
	s_mov_b64 exec, s[8:9]
	s_cbranch_execz .LBB0_11
	s_and_b32 s8, s3, 15
	s_and_b32 s9, s2, 7
	s_lshl_b32 s8, 1, s8
	s_lshl_b32 s9, s9, 2
	v_mov_b32_e32 v1, s9
	v_mov_b32_e32 v2, s8
	global_atomic_or v1, v2, s[34:35] offset:3584
	s_lshl_b32 s3, s3, 8
	s_and_b32 s3, s3, 0xf00
	s_bcnt1_i32_b64 s6, s[6:7]
	v_mov_b32_e32 v1, s3
	v_mov_b32_e32 v2, s6
	global_atomic_add v1, v2, s[64:65] offset:1024

.LBB0_1430:
	s_mov_b64 s[8:9], exec
	s_lshl_b32 s3, s3, 8
	v_mbcnt_lo_u32_b32 v2, s8, 0
	s_add_u32 s6, s4, s3
	v_mbcnt_hi_u32_b32 v2, s9, v2
	s_addc_u32 s7, s5, 0
	v_cmp_eq_u32_e32 vcc, 0, v2
	s_and_saveexec_b64 s[10:11], vcc
	s_cbranch_execz .LBB0_1432
	s_bcnt1_i32_b64 s3, s[8:9]
	v_mov_b32_e32 v4, 0x1000
	v_mov_b32_e32 v5, s3
	s_and_b32 s98, s2, 7
	s_lshl_b32 s98, s98, 2
	v_mov_b32_e32 v252, s98
	global_load_dword v251, v252, s[34:35] offset:3584 sc1
	global_atomic_add v4, v4, v5, s[6:7] offset:1024 sc0

.LBB0_1446:
	s_andn2_saveexec_b64 s[8:9], s[8:9]
	s_cbranch_execz .LBB0_1466
	s_mov_b64 s[8:9], exec
	v_readfirstlane_b32 s98, v251
	s_cmpk_lg_i32 s94, 0x100
	s_cbranch_scc1 xl_glob_b12
	s_bcnt1_i32_b32 s98, s98
	s_cmp_eq_u32 s98, 1
	s_cbranch_scc1 xl_tail_b12
xl_glob_b12:
	buffer_wbl2 sc1
	s_waitcnt lgkmcnt(0)
	s_waitcnt vmcnt(0)
	v_mbcnt_lo_u32_b32 v2, s8, 0
	v_mbcnt_hi_u32_b32 v2, s9, v2
	v_cmp_eq_u32_e32 vcc, 0, v2
	s_and_saveexec_b64 s[10:11], vcc
	s_cbranch_execz .LBB0_1449
	s_bcnt1_i32_b64 s3, s[8:9]
	v_mov_b32_e32 v3, 0x3000
	v_mov_b32_e32 v4, s3
	global_atomic_add v3, v3, v4, s[4:5] offset:1024 sc0

xl_tail_b12:
	s_mov_b64 s[4:5], exec
	v_mbcnt_lo_u32_b32 v1, s4, 0
	v_mbcnt_hi_u32_b32 v1, s5, v1
	v_cmp_eq_u32_e32 vcc, 0, v1
	s_waitcnt vmcnt(0)
	buffer_inv sc1
	s_and_saveexec_b64 s[8:9], vcc
	s_cbranch_execz .LBB0_1465
	s_bcnt1_i32_b64 s3, s[4:5]
	v_mov_b32_e32 v1, 0x2000
	v_mov_b32_e32 v2, s3
	global_atomic_add v1, v2, s[6:7] offset:1024

.LBB0_1518:
	s_andn2_saveexec_b64 s[8:9], s[8:9]
	s_cbranch_execz .LBB0_1538
	s_mov_b64 s[8:9], exec
	v_readfirstlane_b32 s98, v251
	s_cmpk_lg_i32 s94, 0x100
	s_cbranch_scc1 xl_glob_b13
	s_bcnt1_i32_b32 s98, s98
	s_cmp_eq_u32 s98, 1
	s_cbranch_scc1 xl_tail_b13
xl_glob_b13:
	buffer_wbl2 sc1
	s_waitcnt lgkmcnt(0)
	s_waitcnt vmcnt(0)
	v_mbcnt_lo_u32_b32 v2, s8, 0
	v_mbcnt_hi_u32_b32 v2, s9, v2
	v_cmp_eq_u32_e32 vcc, 0, v2
	s_and_saveexec_b64 s[10:11], vcc
	s_cbranch_execz .LBB0_1521
	s_bcnt1_i32_b64 s3, s[8:9]
	v_mov_b32_e32 v3, 0x3000
	v_mov_b32_e32 v4, s3
	global_atomic_add v3, v3, v4, s[4:5] offset:1024 sc0

xl_tail_b13:
	s_mov_b64 s[4:5], exec
	v_mbcnt_lo_u32_b32 v1, s4, 0
	v_mbcnt_hi_u32_b32 v1, s5, v1
	v_cmp_eq_u32_e32 vcc, 0, v1
	s_waitcnt vmcnt(0)
	buffer_inv sc1
	s_and_saveexec_b64 s[8:9], vcc
	s_cbranch_execz .LBB0_1537
	s_bcnt1_i32_b64 s3, s[4:5]
	v_mov_b32_e32 v1, 0x2000
	v_mov_b32_e32 v2, s3
	global_atomic_add v1, v2, s[6:7] offset:1024
